# attention loop: K/V tile loads in scalar-base form (32-bit per-thread offsets + s[94:95]), 64-bit VALU address arithmetic removed (-19 VALU, -10 s_nop per 256 keys); on top of the trimmed SrcC-fold lo
# speedup vs baseline: 1.0110x; 1.0110x over previous
; DI float bflo(unsigned u) { return __uint_as_float(u << 16); }
; DI float bfhi(unsigned u) { return __uint_as_float(u & 0xffff0000u); }
; DI void phase_attn(const Params& p, int hf, bool skipctx, char* smem, int& rot) {
;     ...
;       for (int ks = 0; ks < 6; ++ks) qu[ks] = *(const uint4*)(Qb + tq * 768 + head * 96 + ks * 16 + h * 8);
; #pragma unroll
;       for (int ks = 0; ks < 4; ++ks) {
;         const uint4 u = qu[ks];
;         qf[ks] = pack8(bflo(u.x) * QSCALE, bfhi(u.x) * QSCALE, bflo(u.y) * QSCALE, bfhi(u.y) * QSCALE, bflo(u.z) * QSCALE, bfhi(u.z) * QSCALE, bflo(u.w) * QSCALE, bfhi(u.w) * QSCALE);
;       }
;       const unsigned a1[4] = {qu[4].x, qu[4].y, qu[4].z, qu[4].w}, a2[4] = {qu[5].x, qu[5].y, qu[5].z, qu[5].w};
;       float o1[8], o2[8];
;       const int sq_ = s0 + w * 32 + r;
; #pragma unroll
;       for (int e = 0; e < 8; ++e) {
;         const float x1 = ((e & 1) ? bfhi(a1[e >> 1]) : bflo(a1[e >> 1])) * QSCALE;
;         const float x2 = ((e & 1) ? bfhi(a2[e >> 1]) : bflo(a2[e >> 1])) * QSCALE;
;         float cs = 1.f, sn = 0.f;
;         if (sq_ >= LC) { cs = axc[(sq_ - LC) * 16 + 8 * h + e]; sn = axs[(sq_ - LC) * 16 + 8 * h + e]; }
;         o1[e] = x1 * cs - x2 * sn; o2[e] = x1 * sn + x2 * cs;
;       }
;       qf[4] = pack8(o1[0], o1[1], o1[2], o1[3], o1[4], o1[5], o1[6], o1[7]);
;       qf[5] = pack8(o2[0], o2[1], o2[2], o2[3], o2[4], o2[5], o2[6], o2[7]);
.LBB0_794:
	s_or_b64 exec, exec, s[26:27]
	s_waitcnt vmcnt(0)
	v_lshlrev_b32_e32 v27, 16, v23
	v_lshlrev_b32_e32 v26, 16, v19
	v_pk_mul_f32 v[26:27], v[26:27], s[48:49] op_sel_hi:[1,0]
	v_lshlrev_b32_e32 v47, 16, v22
	v_pk_mul_f32 v[28:29], v[26:27], v[30:31] op_sel:[0,1] op_sel_hi:[1,0]
	v_pk_mul_f32 v[26:27], v[26:27], v[30:31]
	v_and_b32_e32 v30, 0xffff0000, v19
	v_lshlrev_b32_e32 v46, 16, v18
	v_and_b32_e32 v19, 0xffff0000, v22
	v_and_b32_e32 v18, 0xffff0000, v18
	v_and_b32_e32 v31, 0xffff0000, v23
	v_pk_mul_f32 v[46:47], v[46:47], s[48:49] op_sel_hi:[1,0]
	v_pk_mul_f32 v[22:23], v[18:19], s[48:49] op_sel_hi:[1,0]
	v_pk_mul_f32 v[48:49], v[46:47], v[42:43] op_sel:[0,1] op_sel_hi:[1,0]
	v_pk_mul_f32 v[42:43], v[46:47], v[42:43]
	v_pk_mul_f32 v[18:19], v[22:23], v[40:41] op_sel:[0,1] op_sel_hi:[1,0]
	v_pk_mul_f32 v[22:23], v[22:23], v[40:41]
	v_mov_b32_e32 v40, v42
	v_mov_b32_e32 v41, v22
	v_mov_b32_e32 v22, v43
	v_pk_add_f32 v[22:23], v[40:41], v[22:23]
	v_lshlrev_b32_e32 v41, 16, v21
	v_lshlrev_b32_e32 v40, 16, v17
	v_pk_mul_f32 v[40:41], v[40:41], s[48:49] op_sel_hi:[1,0]
	v_mov_b32_e32 v46, v48
	v_mov_b32_e32 v47, v18
	v_mov_b32_e32 v18, v49
	v_pk_mul_f32 v[42:43], v[40:41], v[32:33] op_sel:[0,1] op_sel_hi:[1,0]
	v_pk_mul_f32 v[40:41], v[40:41], v[32:33]
	v_and_b32_e32 v33, 0xffff0000, v21
	v_and_b32_e32 v32, 0xffff0000, v17
	v_pk_add_f32 v[18:19], v[46:47], v[18:19] neg_lo:[0,1] neg_hi:[0,1]
	v_pk_mul_f32 v[46:47], v[32:33], s[48:49] op_sel_hi:[1,0]
	v_mov_b32_e32 v48, v42
	v_pk_mul_f32 v[32:33], v[46:47], v[34:35] op_sel:[0,1] op_sel_hi:[1,0]
	v_pk_mul_f32 v[34:35], v[46:47], v[34:35]
	v_mov_b32_e32 v49, v32
	v_mov_b32_e32 v32, v43
	v_mov_b32_e32 v42, v40
	v_mov_b32_e32 v43, v34
	v_mov_b32_e32 v34, v41
	v_lshlrev_b32_e32 v41, 16, v20
	v_lshlrev_b32_e32 v40, 16, v16
	v_and_b32_e32 v17, 0xffff0000, v20
	v_and_b32_e32 v16, 0xffff0000, v16
	v_pk_mul_f32 v[40:41], v[40:41], s[48:49] op_sel_hi:[1,0]
	v_pk_mul_f32 v[20:21], v[16:17], s[48:49] op_sel_hi:[1,0]
	v_pk_add_f32 v[34:35], v[42:43], v[34:35]
	v_pk_mul_f32 v[42:43], v[40:41], v[38:39] op_sel:[0,1] op_sel_hi:[1,0]
	v_pk_mul_f32 v[38:39], v[40:41], v[38:39]
	v_pk_mul_f32 v[16:17], v[20:21], v[36:37] op_sel:[0,1] op_sel_hi:[1,0]
	v_pk_mul_f32 v[20:21], v[20:21], v[36:37]
	v_mov_b32_e32 v36, v38
	v_mov_b32_e32 v37, v20
	v_mov_b32_e32 v20, v39
	v_pk_add_f32 v[20:21], v[36:37], v[20:21]
	v_lshlrev_b32_e32 v36, 16, v12
	v_and_b32_e32 v37, 0xffff0000, v12
	v_lshlrev_b32_e32 v12, 16, v13
	v_and_b32_e32 v13, 0xffff0000, v13
	v_pk_mul_f32 v[12:13], v[12:13], s[48:49] op_sel_hi:[1,0]
	v_lshlrev_b32_e32 v38, 16, v14
	v_cvt_pk_bf16_f32 v65, v12, v13
	v_lshlrev_b32_e32 v12, 16, v8
	v_and_b32_e32 v13, 0xffff0000, v8
	v_lshlrev_b32_e32 v8, 16, v9
	v_and_b32_e32 v9, 0xffff0000, v9
	v_pk_mul_f32 v[8:9], v[8:9], s[48:49] op_sel_hi:[1,0]
	v_and_b32_e32 v39, 0xffff0000, v14
	v_cvt_pk_bf16_f32 v69, v8, v9
	v_lshlrev_b32_e32 v8, 16, v4
	v_and_b32_e32 v9, 0xffff0000, v4
	v_lshlrev_b32_e32 v4, 16, v5
	v_and_b32_e32 v5, 0xffff0000, v5
	v_lshlrev_b32_e32 v14, 16, v15
	v_and_b32_e32 v15, 0xffff0000, v15
	v_pk_mul_f32 v[4:5], v[4:5], s[48:49] op_sel_hi:[1,0]
	s_mov_b32 s16, 0x2aaaaaab
	v_pk_mul_f32 v[14:15], v[14:15], s[48:49] op_sel_hi:[1,0]
	v_cvt_pk_bf16_f32 v73, v4, v5
	v_mul_hi_i32 v4, v160, s16
	v_cvt_pk_bf16_f32 v67, v14, v15
	v_lshlrev_b32_e32 v14, 16, v10
	v_and_b32_e32 v15, 0xffff0000, v10
	v_lshlrev_b32_e32 v10, 16, v11
	v_and_b32_e32 v11, 0xffff0000, v11
	v_lshrrev_b32_e32 v5, 31, v4
	v_ashrrev_i32_e32 v4, 1, v4
	v_pk_mul_f32 v[10:11], v[10:11], s[48:49] op_sel_hi:[1,0]
	v_add_u32_e32 v45, v4, v5
	v_cvt_pk_bf16_f32 v71, v10, v11
	v_lshlrev_b32_e32 v10, 16, v6
	v_and_b32_e32 v11, 0xffff0000, v6
	v_lshlrev_b32_e32 v6, 16, v7
	v_and_b32_e32 v7, 0xffff0000, v7
	v_mad_u64_u32 v[4:5], s[38:39], v45, -12, v[160:161]
	v_add_u32_e32 v164, 0x200, v160
	v_pk_mul_f32 v[6:7], v[6:7], s[48:49] op_sel_hi:[1,0]
	v_mul_hi_i32 v5, v164, s16
	v_cvt_pk_bf16_f32 v75, v6, v7
	v_lshrrev_b32_e32 v6, 31, v5
	v_ashrrev_i32_e32 v5, 1, v5
	s_mul_i32 s15, s4, 0xcc000
	v_add_u32_e32 v5, v5, v6
	v_pk_mul_f32 v[38:39], v[38:39], s[48:49] op_sel_hi:[1,0]
	v_pk_mul_f32 v[14:15], v[14:15], s[48:49] op_sel_hi:[1,0]
	s_mul_hi_i32 s5, s4, 0xcc000
	s_add_u32 s26, s90, s15
	v_mad_u64_u32 v[6:7], s[38:39], v5, -12, v[164:165]
	v_add_u32_e32 v162, 0x400, v160
	v_cvt_pk_bf16_f32 v66, v38, v39
	v_cvt_pk_bf16_f32 v70, v14, v15
	v_pk_mul_f32 v[8:9], v[8:9], s[48:49] op_sel_hi:[1,0]
	v_pk_mul_f32 v[10:11], v[10:11], s[48:49] op_sel_hi:[1,0]
	s_addc_u32 s27, s91, s5
	v_mul_hi_i32 v7, v162, s16
	v_lshlrev_b32_e32 v14, 3, v4
	v_lshlrev_b32_e32 v38, 3, v6
	v_pk_mul_f32 v[36:37], v[36:37], s[48:49] op_sel_hi:[1,0]
	v_pk_mul_f32 v[12:13], v[12:13], s[48:49] op_sel_hi:[1,0]
	v_cvt_pk_bf16_f32 v72, v8, v9
	v_cvt_pk_bf16_f32 v74, v10, v11
	v_lshrrev_b32_e32 v8, 31, v7
	v_ashrrev_i32_e32 v7, 1, v7
	v_mov_b64_e32 v[10:11], s[26:27]
	v_ashrrev_i32_e32 v15, 31, v14
	v_ashrrev_i32_e32 v39, 31, v38
	v_cvt_pk_bf16_f32 v64, v36, v37
	v_cvt_pk_bf16_f32 v68, v12, v13
	v_add_u32_e32 v7, v7, v8
	v_mad_i64_i32 v[12:13], s[26:27], v45, s17, v[10:11]
	v_lshlrev_b64 v[14:15], 1, v[14:15]
	v_mad_i64_i32 v[36:37], s[26:27], v5, s17, v[10:11]
	v_lshlrev_b64 v[38:39], 1, v[38:39]
	v_mad_u64_u32 v[8:9], s[38:39], v7, -12, v[162:163]
	v_lshl_add_u64 v[12:13], v[12:13], 0, v[14:15]
	v_lshl_add_u64 v[36:37], v[36:37], 0, v[38:39]
	s_barrier
; DI f32x16 zero16() { f32x16 z; for (int i = 0; i < 16; ++i) z[i] = 0.f; return z; }
; DI void phase_attn(const Params& p, int hf, bool skipctx, char* smem, int& rot) {
;     ...
;     f32x16 o[2]; o[0] = zero16(); o[1] = zero16();
;     float m_run = -1e30f, l_run = 0.f;
;     uint4 ak0, ak1, ak2, av0, av1, bk0, bk1, bk2, bv0, bv1;
;     const int kr0 = tid / 12, kc0 = tid - kr0 * 12, kr1 = (tid + 512) / 12, kc1 = (tid + 512) - kr1 * 12, kr2 = (tid + 1024) / 12, kc2 = (tid + 1024) - kr2 * 12;
;     const int vr0 = tid >> 4, vr1 = (tid + 512) >> 4, vc = tid & 15;
;     ...
;     __syncthreads();
;     ATT_LOAD(ak0, ak1, ak2, av0, av1, 0);
;     ATT_LOAD(bk0, bk1, bk2, bv0, bv1, 1);
;     ATT_WRITE(ak0, ak1, ak2, av0, av1, 0);
;     __syncthreads();
	global_load_dwordx4 v[76:79], v[12:13], off
	global_load_dwordx4 v[80:83], v[36:37], off
	v_lshlrev_b32_e32 v36, 3, v8
	s_mul_i32 s15, s4, 0x88000
	v_readlane_b32 s36, v252, 5
	v_ashrrev_i32_e32 v37, 31, v36
	s_mul_hi_i32 s5, s4, 0x88000
	v_readlane_b32 s37, v252, 6
	s_add_u32 s36, s36, s15
	v_mad_i64_i32 v[12:13], s[26:27], v7, s17, v[10:11]
	v_lshlrev_b64 v[36:37], 1, v[36:37]
	s_addc_u32 s37, s37, s5
	v_lshl_add_u64 v[12:13], v[12:13], 0, v[36:37]
	v_mov_b32_e32 v40, v42
	v_mov_b32_e32 v41, v16
	v_mov_b32_e32 v16, v43
	v_ashrrev_i32_e32 v9, 4, v160
	v_ashrrev_i32_e32 v50, 4, v164
	global_load_dwordx4 v[84:87], v[12:13], off
	v_mov_b64_e32 v[12:13], s[36:37]
	s_movk_i32 s16, 0x2200
	v_lshlrev_b32_e32 v165, 4, v160
	v_cvt_pk_bf16_f32 v100, v20, v21
	v_add_u32_e32 v20, 0x80, v5
	v_pk_add_f32 v[16:17], v[40:41], v[16:17] neg_lo:[0,1] neg_hi:[0,1]
	v_mad_i64_i32 v[40:41], s[26:27], v9, s16, v[12:13]
	v_and_b32_e32 v42, 0xf0, v165
	v_mov_b32_e32 v43, v221
	v_mad_i64_i32 v[12:13], s[26:27], v50, s16, v[12:13]
	v_cvt_pk_bf16_f32 v98, v18, v19
	v_cvt_pk_bf16_f32 v102, v22, v23
	v_add_u32_e32 v18, 0x80, v45
	v_mad_i64_i32 v[20:21], s[26:27], v20, s17, v[10:11]
	v_add_u32_e32 v22, 0x80, v7
	v_lshl_add_u64 v[40:41], v[40:41], 0, v[42:43]
	v_lshl_add_u64 v[12:13], v[12:13], 0, v[42:43]
	v_mad_i64_i32 v[18:19], s[26:27], v18, s17, v[10:11]
	v_lshl_add_u64 v[20:21], v[20:21], 0, v[38:39]
	v_mad_i64_i32 v[10:11], s[26:27], v22, s17, v[10:11]
	global_load_dwordx4 v[92:95], v[40:41], off
	global_load_dwordx4 v[104:107], v[12:13], off
	v_lshl_add_u64 v[18:19], v[18:19], 0, v[14:15]
	v_lshl_add_u64 v[10:11], v[10:11], 0, v[36:37]
	global_load_dwordx4 v[108:111], v[20:21], off
	global_load_dwordx4 v[116:119], v[10:11], off
	global_load_dwordx4 v[120:123], v[40:41], off offset:256
	global_load_dwordx4 v[112:115], v[18:19], off
	global_load_dwordx4 v[124:127], v[12:13], off offset:256
	v_lshlrev_b32_e32 v46, 16, v0
	v_and_b32_e32 v47, 0xffff0000, v0
	v_lshlrev_b32_e32 v0, 16, v1
	v_and_b32_e32 v1, 0xffff0000, v1
	v_pk_mul_f32 v[30:31], v[30:31], s[48:49] op_sel_hi:[1,0]
	v_pk_add_f32 v[32:33], v[48:49], v[32:33] neg_lo:[0,1] neg_hi:[0,1]
	v_pk_mul_f32 v[0:1], v[0:1], s[48:49] op_sel_hi:[1,0]
	v_lshlrev_b32_e32 v48, 16, v2
	v_and_b32_e32 v49, 0xffff0000, v2
	v_lshlrev_b32_e32 v2, 16, v3
	v_and_b32_e32 v3, 0xffff0000, v3
	v_pk_mul_f32 v[2:3], v[2:3], s[48:49] op_sel_hi:[1,0]
	v_cvt_pk_bf16_f32 v89, v0, v1
	v_pk_mul_f32 v[0:1], v[30:31], v[24:25] op_sel:[0,1] op_sel_hi:[1,0]
	v_cvt_pk_bf16_f32 v91, v2, v3
	v_mov_b32_e32 v2, v28
	v_mov_b32_e32 v3, v0
	v_mov_b32_e32 v0, v29
	v_pk_add_f32 v[0:1], v[2:3], v[0:1] neg_lo:[0,1] neg_hi:[0,1]
	v_pk_mul_f32 v[2:3], v[30:31], v[24:25]
	v_mul_lo_u32 v10, v45, s97
	v_mov_b32_e32 v24, v26
	v_mov_b32_e32 v25, v2
	v_mov_b32_e32 v2, v27
	v_add_u32_e32 v10, 0, v10
	v_lshlrev_b32_e32 v4, 4, v4
	v_pk_add_f32 v[2:3], v[24:25], v[2:3]
	v_add_u32_e32 v176, v10, v4
	v_mul_lo_u32 v4, v5, s97
	v_cvt_pk_bf16_f32 v103, v2, v3
	v_mad_i64_i32 v[2:3], s[26:27], v5, s17, 0
	v_add_u32_e32 v4, 0, v4
	v_lshlrev_b32_e32 v5, 4, v6
	v_add_u32_e32 v177, v4, v5
	v_mul_lo_u32 v4, v7, s97
	v_add_u32_e32 v4, 0, v4
	v_lshlrev_b32_e32 v5, 4, v8
	s_movk_i32 s20, 0x108
	v_cvt_pk_bf16_f32 v96, v16, v17
	v_cvt_pk_bf16_f32 v99, v0, v1
	v_mad_i64_i32 v[0:1], s[26:27], v45, s17, 0
	v_mad_i64_i32 v[16:17], s[26:27], v7, s17, 0
	v_add_u32_e32 v178, v4, v5
	v_mul_lo_u32 v4, v9, s20
	v_add_u32_e32 v5, 0, v4
	s_movk_i32 s26, 0x6800
	v_add3_u32 v179, v5, v42, s26
	v_mul_lo_u32 v5, v50, s20
	v_add_u32_e32 v6, 0, v5
	v_add3_u32 v180, v6, v42, s26
	v_or_b32_e32 v181, 32, v161
	v_or_b32_e32 v182, 64, v161
	v_or_b32_e32 v183, 0x60, v161
	v_readlane_b32 s26, v254, 35
	v_mul_u32_u24_e32 v19, 0x108, v44
	v_mad_u32_u24 v18, v44, s97, 0
	v_add_u32_e32 v21, s26, v4
	v_add_u32_e32 v22, s26, v5
	v_add_u32_e32 v23, s26, v161
	v_add_u32_e32 v24, s26, v181
	v_mov_b32_e32 v4, s26
	v_add_u32_e32 v25, s26, v182
	v_add_u32_e32 v26, s26, v183
	v_readlane_b32 s26, v254, 36
	v_mad_u32_u24 v184, v44, s20, v4
	v_add_u32_e32 v20, 0, v161
	v_add_u32_e32 v27, s26, v161
	v_add_u32_e32 v28, s26, v181
	v_mov_b32_e32 v4, s26
	v_add_u32_e32 v29, s26, v182
	v_add_u32_e32 v30, s26, v183
	s_add_u32 s26, s15, 0x1a49c300
	s_addc_u32 s27, s5, 0
	v_mad_u32_u24 v185, v44, s20, v4
	v_mov_b64_e32 v[4:5], s[26:27]
	v_mad_i64_i32 v[166:167], s[26:27], v9, s16, v[4:5]
	v_mad_i64_i32 v[168:169], s[26:27], v50, s16, v[4:5]
	v_mad_i64_i32 v[4:5], s[26:27], s4, v231, v[16:17]
	v_mad_i64_i32 v[2:3], s[26:27], s4, v231, v[2:3]
	v_mad_i64_i32 v[0:1], s[4:5], s4, v231, v[0:1]
	v_lshl_add_u64 v[174:175], v[0:1], 0, v[14:15]
	v_mov_b32_e32 v14, v221
	v_mov_b32_e32 v15, v221
	v_add_u32_e32 v186, v21, v42
	v_add_u32_e32 v187, v22, v42
	v_add_u32_e32 v188, v23, v19
	v_add_u32_e32 v16, v24, v19
	v_add_u32_e32 v17, v25, v19
	v_add_u32_e32 v21, v26, v19
	v_add_u32_e32 v22, v28, v19
	v_add_u32_e32 v23, v29, v19
	v_add_u32_e32 v24, v30, v19
	v_pk_mul_f32 v[46:47], v[46:47], s[48:49] op_sel_hi:[1,0]
	v_pk_mul_f32 v[48:49], v[48:49], s[48:49] op_sel_hi:[1,0]
	v_lshl_add_u64 v[170:171], v[4:5], 0, v[36:37]
	v_lshl_add_u64 v[172:173], v[2:3], 0, v[38:39]
	v_mov_b32_e32 v0, v221
	v_mov_b32_e32 v1, v221
	v_mov_b32_e32 v2, v221
	v_mov_b32_e32 v3, v221
	v_mov_b32_e32 v4, v221
	v_mov_b32_e32 v5, v221
	v_mov_b32_e32 v6, v221
	v_mov_b32_e32 v7, v221
	v_mov_b32_e32 v8, v221
	v_mov_b32_e32 v9, v221
	v_mov_b32_e32 v10, v221
	v_mov_b32_e32 v11, v221
	v_mov_b32_e32 v12, v221
	v_mov_b32_e32 v13, v221
	v_add_u32_e32 v189, v27, v19
	v_add_u32_e32 v190, v18, v220
	v_add_u32_e32 v191, v20, v19
	v_add_u32_e32 v194, 0x2000, v16
	v_add_u32_e32 v204, 0x2000, v17
	v_add_u32_e32 v206, 0x2000, v21
	v_add_u32_e32 v208, 0x2000, v22
	v_add_u32_e32 v210, 0x2000, v23
	v_add_u32_e32 v211, 0x2000, v24
	v_mov_b64_e32 v[30:31], v[14:15]
	v_cvt_pk_bf16_f32 v88, v46, v47
	v_cvt_pk_bf16_f32 v90, v48, v49
	v_cvt_pk_bf16_f32 v97, v32, v33
	v_cvt_pk_bf16_f32 v101, v34, v35
	v_or_b32_e32 v166, v166, v42
	v_or_b32_e32 v168, v168, v42
	s_mov_b32 s4, 0
	v_mov_b32_e32 v212, 0xf149f2ca
	v_mov_b32_e32 v213, 0
	v_mov_b64_e32 v[28:29], v[12:13]
	v_mov_b64_e32 v[26:27], v[10:11]
	v_mov_b64_e32 v[24:25], v[8:9]
	v_mov_b64_e32 v[22:23], v[6:7]
	v_mov_b64_e32 v[20:21], v[4:5]
	v_mov_b64_e32 v[18:19], v[2:3]
	v_mov_b64_e32 v[16:17], v[0:1]
	v_and_b32_e32 v200, 15, v192
	v_lshrrev_b32_e32 v201, 4, v192
	v_mul_u32_u24_e32 v179, 0x110, v201
	v_lshrrev_b32_e32 v202, 1, v200
	v_lshl_add_u32 v179, v202, 5, v179
	v_and_b32_e32 v202, 1, v200
	v_lshl_add_u32 v179, v202, 3, v179
	v_add_u32_e32 v179, 0x6800, v179
	v_add_u32_e32 v180, 0x2200, v179
	v_add_u32_e32 v186, 0xac00, v179
	v_add_u32_e32 v187, 0xac00, v180
	v_and_b32_e32 v200, 31, v192
	v_bfe_u32 v201, v192, 5, 1
	v_mul_u32_u24_e32 v191, 0x110, v200
	v_lshl_add_u32 v191, v201, 4, v191
	v_add_u32_e32 v191, 0x6800, v191
	s_waitcnt vmcnt(9)
; DI void phase_attn(const Params& p, int hf, bool skipctx, char* smem, int& rot) {
;     ...
;     ATT_WRITE(ak0, ak1, ak2, av0, av1, 0);
;     __syncthreads();
;     for (int kt = 0; kt < nkt; kt += 2) {
;       if (kt + 2 < nkt) ATT_LOAD(ak0, ak1, ak2, av0, av1, kt + 2);
	ds_write_b128 v176, v[76:79]
	s_waitcnt vmcnt(8)
	ds_write_b128 v177, v[80:83]
	s_waitcnt vmcnt(7)
	ds_write_b128 v178, v[84:87]
	s_waitcnt vmcnt(6)
	ds_write_b64 v179, v[92:93] offset:0
	ds_write_b64 v179, v[94:95] offset:16
	s_waitcnt vmcnt(5)
	ds_write_b64 v179, v[104:105] offset:8704
	ds_write_b64 v179, v[106:107] offset:8720
	s_waitcnt lgkmcnt(0)
	s_barrier
	v_mov_b32_e32 v194, v176
	v_mov_b32_e32 v204, v177
	v_mov_b32_e32 v206, v178
	v_mov_b32_e32 v208, v179
	v_mov_b32_e32 v210, v190
	v_mov_b32_e32 v211, v191
	v_mov_b32_e32 v220, 0xf149f2ca
	v_mov_b32_e32 v176, 0
	v_mov_b32_e32 v177, 0
	v_mov_b32_e32 v178, 0
	v_mov_b32_e32 v179, 0
	v_mov_b32_e32 v180, 0
	v_mov_b32_e32 v181, 0
	v_mov_b32_e32 v182, 0
	v_mov_b32_e32 v183, 0
	v_mov_b32_e32 v184, 0
	v_mov_b32_e32 v185, 0
	v_mov_b32_e32 v186, 0
	v_mov_b32_e32 v187, 0
	v_mov_b32_e32 v188, 0
	v_mov_b32_e32 v189, 0
	v_mov_b32_e32 v190, 0
	v_mov_b32_e32 v191, 0
	v_add_u32_e32 v170, 0x18b28000, v170
	v_add_u32_e32 v172, 0x18b28000, v172
	v_add_u32_e32 v174, 0x18b28000, v174
.LBB0_795:
	ds_read_b128 v[32:35], v210
	ds_read_b128 v[128:131], v210 offset:32
	ds_read_b128 v[132:135], v210 offset:64
	ds_read_b128 v[136:139], v210 offset:96
	ds_read_b128 v[140:143], v210 offset:128
	ds_read_b128 v[144:147], v210 offset:160
	ds_read_b128 v[36:39], v210 offset:6656
	ds_read_b128 v[148:151], v210 offset:6688
	ds_read_b128 v[152:155], v210 offset:6720
	ds_read_b128 v[156:159], v210 offset:6752
	ds_read_b128 v[214:217], v210 offset:6784
	ds_read_b128 v[234:237], v210 offset:6816
	s_add_i32 s15, s4, 2
	s_cmp_lt_u32 s15, s13
	s_cselect_b64 s[36:37], -1, 0
	s_cmp_ge_u32 s15, s13
	s_cselect_b64 s[26:27], -1, 0
	s_and_b64 vcc, exec, s[26:27]
	s_cbranch_vccnz .LBB0_797
	global_load_dwordx4 v[76:79], v174, s[94:95]
	global_load_dwordx4 v[80:83], v172, s[94:95]
	global_load_dwordx4 v[84:87], v170, s[94:95]
	global_load_dwordx4 v[92:95], v166, s[94:95] offset:-256
	global_load_dwordx4 v[104:107], v168, s[94:95] offset:-256

; #define MFMA(a, b, c) __builtin_amdgcn_mfma_f32_32x32x16_bf16((a), (b), (c), 0, 0, 0)
; DI float fexp2(float x) { return __builtin_amdgcn_exp2f(x); }
; DI void phase_attn(const Params& p, int hf, bool skipctx, char* smem, int& rot) {
;     ...
;       float ps = 0.f;
; #pragma unroll
;       for (int kb = 0; kb < 2; ++kb)
; #pragma unroll
;         for (int i = 0; i < 16; ++i) { const float e = fexp2(st[kb][i] - m_run); st[kb][i] = e; ps += e; }
;       l_run += ps;
; #pragma unroll
;       for (int kb = 0; kb < 2; ++kb)
; #pragma unroll
;         for (int s2 = 0; s2 < 2; ++s2) {
;           const bf16x8 pb = pack8(st[kb][8 * s2 + 0], st[kb][8 * s2 + 1], st[kb][8 * s2 + 2], st[kb][8 * s2 + 3], st[kb][8 * s2 + 4], st[kb][8 * s2 + 5], st[kb][8 * s2 + 6], st[kb][8 * s2 + 7]);
; #pragma unroll
;           for (int dvb = 0; dvb < 2; ++dvb) o[dvb] = MFMA(vf[kb][s2][dvb], pb, o[dvb]);
;         }
;     };
;     __syncthreads();
;     ATT_LOAD(ak0, ak1, ak2, av0, av1, 0);
;     ATT_LOAD(bk0, bk1, bk2, bv0, bv1, 1);
;     ATT_WRITE(ak0, ak1, ak2, av0, av1, 0);
;     __syncthreads();
;     for (int kt = 0; kt < nkt; kt += 2) {
;       if (kt + 2 < nkt) ATT_LOAD(ak0, ak1, ak2, av0, av1, kt + 2);
;       compute(0, 0); compute(0, 1);
;       ATT_WRITE(bk0, bk1, bk2, bv0, bv1, 1);
;       __syncthreads();
;       if (kt + 3 < nkt) ATT_LOAD(bk0, bk1, bk2, bv0, bv1, kt + 3);
.LBB0_801:
	v_exp_f32_e32 v48, v48
	v_exp_f32_e32 v49, v49
	v_exp_f32_e32 v50, v50
	v_exp_f32_e32 v51, v51
	v_exp_f32_e32 v52, v52
	v_exp_f32_e32 v53, v53
	v_exp_f32_e32 v54, v54
	v_exp_f32_e32 v55, v55
	v_cvt_pk_bf16_f32 v214, v48, v49
	v_cvt_pk_bf16_f32 v215, v50, v51
	v_cvt_pk_bf16_f32 v216, v52, v53
	v_cvt_pk_bf16_f32 v217, v54, v55
	s_waitcnt lgkmcnt(7)
	s_nop 0
	v_mfma_f32_32x32x16_bf16 v[16:31], v[156:159], v[214:217], v[16:31]
	v_exp_f32_e32 v56, v56
	s_waitcnt lgkmcnt(5)
	v_mfma_f32_32x32x16_bf16 v[0:15], v[152:155], v[214:217], v[0:15]
	v_exp_f32_e32 v57, v57
	v_exp_f32_e32 v58, v58
	v_exp_f32_e32 v59, v59
	v_exp_f32_e32 v60, v60
	v_exp_f32_e32 v61, v61
	v_exp_f32_e32 v62, v62
	v_exp_f32_e32 v63, v63
	v_cvt_pk_bf16_f32 v152, v56, v57
	v_cvt_pk_bf16_f32 v153, v58, v59
	v_cvt_pk_bf16_f32 v154, v60, v61
	v_cvt_pk_bf16_f32 v155, v62, v63
	s_nop 1
	v_mfma_f32_32x32x16_bf16 v[16:31], v[148:151], v[152:155], v[16:31]
	v_exp_f32_e32 v32, v32
	s_waitcnt lgkmcnt(4)
	v_mfma_f32_32x32x16_bf16 v[0:15], v[144:147], v[152:155], v[0:15]
	v_exp_f32_e32 v33, v33
	v_exp_f32_e32 v34, v34
	v_exp_f32_e32 v35, v35
	v_exp_f32_e32 v36, v36
	v_exp_f32_e32 v37, v37
	v_exp_f32_e32 v38, v38
	v_exp_f32_e32 v39, v39
	v_cvt_pk_bf16_f32 v144, v32, v33
	v_cvt_pk_bf16_f32 v145, v34, v35
	v_cvt_pk_bf16_f32 v146, v36, v37
	v_cvt_pk_bf16_f32 v147, v38, v39
	s_waitcnt lgkmcnt(3)
	s_nop 0
	v_mfma_f32_32x32x16_bf16 v[16:31], v[140:143], v[144:147], v[16:31]
	v_exp_f32_e32 v40, v40
	s_waitcnt lgkmcnt(2)
	v_mfma_f32_32x32x16_bf16 v[0:15], v[136:139], v[144:147], v[0:15]
	v_exp_f32_e32 v41, v41
	v_exp_f32_e32 v42, v42
	v_exp_f32_e32 v43, v43
	v_exp_f32_e32 v44, v44
	v_exp_f32_e32 v45, v45
	v_exp_f32_e32 v46, v46
	v_exp_f32_e32 v47, v47
	v_cvt_pk_bf16_f32 v136, v40, v41
	v_cvt_pk_bf16_f32 v137, v42, v43
	v_cvt_pk_bf16_f32 v138, v44, v45
	v_cvt_pk_bf16_f32 v139, v46, v47
	s_add_i32 s4, s4, 3
	s_cmp_ge_u32 s4, s13
	s_waitcnt lgkmcnt(1)
	v_mfma_f32_32x32x16_bf16 v[16:31], v[128:131], v[136:139], v[16:31]
	s_waitcnt vmcnt(1)
	ds_write_b128 v194, v[112:115] offset:44032
	ds_write_b128 v204, v[108:111] offset:44032
	ds_write_b128 v206, v[116:119] offset:44032
	ds_write_b64 v208, v[120:121] offset:44032
	ds_write_b64 v208, v[122:123] offset:44048
	s_waitcnt vmcnt(0)
	ds_write_b64 v208, v[124:125] offset:52736
	ds_write_b64 v208, v[126:127] offset:52752
	s_waitcnt lgkmcnt(0)
	s_barrier
	v_mfma_f32_32x32x16_bf16 v[0:15], v[132:135], v[136:139], v[0:15]
	s_cbranch_scc1 .LBB0_803
	v_add_u32_e32 v200, 0x6000, v174
	v_add_u32_e32 v201, 0x6000, v172
	v_add_u32_e32 v202, 0x6000, v170
	global_load_dwordx4 v[112:115], v200, s[94:95]
	global_load_dwordx4 v[108:111], v201, s[94:95]
	global_load_dwordx4 v[116:119], v202, s[94:95]
	global_load_dwordx4 v[120:123], v166, s[94:95]
	global_load_dwordx4 v[124:127], v168, s[94:95]

; DI float bflo(unsigned u) { return __uint_as_float(u << 16); }
; DI float bfhi(unsigned u) { return __uint_as_float(u & 0xffff0000u); }
; DI void phase_attn(const Params& p, int hf, bool skipctx, char* smem, int& rot) {
;     ...
;       for (int ks = 0; ks < 6; ++ks) qu[ks] = *(const uint4*)(Qb + tq * 768 + head * 96 + ks * 16 + h * 8);
; #pragma unroll
;       for (int ks = 0; ks < 4; ++ks) {
;         const uint4 u = qu[ks];
;         qf[ks] = pack8(bflo(u.x) * QSCALE, bfhi(u.x) * QSCALE, bflo(u.y) * QSCALE, bfhi(u.y) * QSCALE, bflo(u.z) * QSCALE, bfhi(u.z) * QSCALE, bflo(u.w) * QSCALE, bfhi(u.w) * QSCALE);
;       }
;       const unsigned a1[4] = {qu[4].x, qu[4].y, qu[4].z, qu[4].w}, a2[4] = {qu[5].x, qu[5].y, qu[5].z, qu[5].w};
;       float o1[8], o2[8];
;       const int sq_ = s0 + w * 32 + r;
; #pragma unroll
;       for (int e = 0; e < 8; ++e) {
;         const float x1 = ((e & 1) ? bfhi(a1[e >> 1]) : bflo(a1[e >> 1])) * QSCALE;
;         const float x2 = ((e & 1) ? bfhi(a2[e >> 1]) : bflo(a2[e >> 1])) * QSCALE;
;         float cs = 1.f, sn = 0.f;
;         if (sq_ >= LC) { cs = axc[(sq_ - LC) * 16 + 8 * h + e]; sn = axs[(sq_ - LC) * 16 + 8 * h + e]; }
;         o1[e] = x1 * cs - x2 * sn; o2[e] = x1 * sn + x2 * cs;
;       }
;       qf[4] = pack8(o1[0], o1[1], o1[2], o1[3], o1[4], o1[5], o1[6], o1[7]);
;       qf[5] = pack8(o2[0], o2[1], o2[2], o2[3], o2[4], o2[5], o2[6], o2[7]);
.LBB0_1059:
	s_or_b64 exec, exec, s[26:27]
	s_waitcnt vmcnt(0)
	v_lshlrev_b32_e32 v27, 16, v23
	v_lshlrev_b32_e32 v26, 16, v19
	v_pk_mul_f32 v[26:27], v[26:27], s[48:49] op_sel_hi:[1,0]
	v_lshlrev_b32_e32 v47, 16, v22
	v_pk_mul_f32 v[28:29], v[26:27], v[30:31] op_sel:[0,1] op_sel_hi:[1,0]
	v_pk_mul_f32 v[26:27], v[26:27], v[30:31]
	v_and_b32_e32 v30, 0xffff0000, v19
	v_lshlrev_b32_e32 v46, 16, v18
	v_and_b32_e32 v19, 0xffff0000, v22
	v_and_b32_e32 v18, 0xffff0000, v18
	v_and_b32_e32 v31, 0xffff0000, v23
	v_pk_mul_f32 v[46:47], v[46:47], s[48:49] op_sel_hi:[1,0]
	v_pk_mul_f32 v[22:23], v[18:19], s[48:49] op_sel_hi:[1,0]
	v_pk_mul_f32 v[48:49], v[46:47], v[42:43] op_sel:[0,1] op_sel_hi:[1,0]
	v_pk_mul_f32 v[42:43], v[46:47], v[42:43]
	v_pk_mul_f32 v[18:19], v[22:23], v[40:41] op_sel:[0,1] op_sel_hi:[1,0]
	v_pk_mul_f32 v[22:23], v[22:23], v[40:41]
	v_mov_b32_e32 v40, v42
	v_mov_b32_e32 v41, v22
	v_mov_b32_e32 v22, v43
	v_pk_add_f32 v[22:23], v[40:41], v[22:23]
	v_lshlrev_b32_e32 v41, 16, v21
	v_lshlrev_b32_e32 v40, 16, v17
	v_pk_mul_f32 v[40:41], v[40:41], s[48:49] op_sel_hi:[1,0]
	v_mov_b32_e32 v46, v48
	v_mov_b32_e32 v47, v18
	v_mov_b32_e32 v18, v49
	v_pk_mul_f32 v[42:43], v[40:41], v[32:33] op_sel:[0,1] op_sel_hi:[1,0]
	v_pk_mul_f32 v[40:41], v[40:41], v[32:33]
	v_and_b32_e32 v33, 0xffff0000, v21
	v_and_b32_e32 v32, 0xffff0000, v17
	v_pk_add_f32 v[18:19], v[46:47], v[18:19] neg_lo:[0,1] neg_hi:[0,1]
	v_pk_mul_f32 v[46:47], v[32:33], s[48:49] op_sel_hi:[1,0]
	v_mov_b32_e32 v48, v42
	v_pk_mul_f32 v[32:33], v[46:47], v[34:35] op_sel:[0,1] op_sel_hi:[1,0]
	v_pk_mul_f32 v[34:35], v[46:47], v[34:35]
	v_mov_b32_e32 v49, v32
	v_mov_b32_e32 v32, v43
	v_mov_b32_e32 v42, v40
	v_mov_b32_e32 v43, v34
	v_mov_b32_e32 v34, v41
	v_lshlrev_b32_e32 v41, 16, v20
	v_lshlrev_b32_e32 v40, 16, v16
	v_and_b32_e32 v17, 0xffff0000, v20
	v_and_b32_e32 v16, 0xffff0000, v16
	v_pk_mul_f32 v[40:41], v[40:41], s[48:49] op_sel_hi:[1,0]
	v_pk_mul_f32 v[20:21], v[16:17], s[48:49] op_sel_hi:[1,0]
	v_pk_add_f32 v[34:35], v[42:43], v[34:35]
	v_pk_mul_f32 v[42:43], v[40:41], v[38:39] op_sel:[0,1] op_sel_hi:[1,0]
	v_pk_mul_f32 v[38:39], v[40:41], v[38:39]
	v_pk_mul_f32 v[16:17], v[20:21], v[36:37] op_sel:[0,1] op_sel_hi:[1,0]
	v_pk_mul_f32 v[20:21], v[20:21], v[36:37]
	v_mov_b32_e32 v36, v38
	v_mov_b32_e32 v37, v20
	v_mov_b32_e32 v20, v39
	v_pk_add_f32 v[20:21], v[36:37], v[20:21]
	v_lshlrev_b32_e32 v36, 16, v12
	v_and_b32_e32 v37, 0xffff0000, v12
	v_lshlrev_b32_e32 v12, 16, v13
	v_and_b32_e32 v13, 0xffff0000, v13
	v_pk_mul_f32 v[12:13], v[12:13], s[48:49] op_sel_hi:[1,0]
	v_lshlrev_b32_e32 v38, 16, v14
	v_cvt_pk_bf16_f32 v65, v12, v13
	v_lshlrev_b32_e32 v12, 16, v8
	v_and_b32_e32 v13, 0xffff0000, v8
	v_lshlrev_b32_e32 v8, 16, v9
	v_and_b32_e32 v9, 0xffff0000, v9
	v_pk_mul_f32 v[8:9], v[8:9], s[48:49] op_sel_hi:[1,0]
	v_and_b32_e32 v39, 0xffff0000, v14
	v_cvt_pk_bf16_f32 v69, v8, v9
	v_lshlrev_b32_e32 v8, 16, v4
	v_and_b32_e32 v9, 0xffff0000, v4
	v_lshlrev_b32_e32 v4, 16, v5
	v_and_b32_e32 v5, 0xffff0000, v5
	v_lshlrev_b32_e32 v14, 16, v15
	v_and_b32_e32 v15, 0xffff0000, v15
	v_pk_mul_f32 v[4:5], v[4:5], s[48:49] op_sel_hi:[1,0]
	s_mov_b32 s29, 0x2aaaaaab
	v_pk_mul_f32 v[14:15], v[14:15], s[48:49] op_sel_hi:[1,0]
	v_cvt_pk_bf16_f32 v73, v4, v5
	v_mul_hi_i32 v4, v160, s29
	v_cvt_pk_bf16_f32 v67, v14, v15
	v_lshlrev_b32_e32 v14, 16, v10
	v_and_b32_e32 v15, 0xffff0000, v10
	v_lshlrev_b32_e32 v10, 16, v11
	v_and_b32_e32 v11, 0xffff0000, v11
	v_lshrrev_b32_e32 v5, 31, v4
	v_ashrrev_i32_e32 v4, 1, v4
	v_pk_mul_f32 v[10:11], v[10:11], s[48:49] op_sel_hi:[1,0]
	v_add_u32_e32 v45, v4, v5
	v_cvt_pk_bf16_f32 v71, v10, v11
	v_lshlrev_b32_e32 v10, 16, v6
	v_and_b32_e32 v11, 0xffff0000, v6
	v_lshlrev_b32_e32 v6, 16, v7
	v_and_b32_e32 v7, 0xffff0000, v7
	v_mad_u64_u32 v[4:5], s[38:39], v45, -12, v[160:161]
	v_add_u32_e32 v164, 0x200, v160
	v_pk_mul_f32 v[6:7], v[6:7], s[48:49] op_sel_hi:[1,0]
	v_mul_hi_i32 v5, v164, s29
	v_cvt_pk_bf16_f32 v75, v6, v7
	v_lshrrev_b32_e32 v6, 31, v5
	v_ashrrev_i32_e32 v5, 1, v5
	s_mul_i32 s15, s4, 0xcc000
	v_add_u32_e32 v5, v5, v6
	v_pk_mul_f32 v[38:39], v[38:39], s[48:49] op_sel_hi:[1,0]
	v_pk_mul_f32 v[14:15], v[14:15], s[48:49] op_sel_hi:[1,0]
	s_mul_hi_i32 s5, s4, 0xcc000
	s_add_u32 s26, s90, s15
	v_mad_u64_u32 v[6:7], s[38:39], v5, -12, v[164:165]
	v_add_u32_e32 v162, 0x400, v160
	v_cvt_pk_bf16_f32 v66, v38, v39
	v_cvt_pk_bf16_f32 v70, v14, v15
	v_pk_mul_f32 v[8:9], v[8:9], s[48:49] op_sel_hi:[1,0]
	v_pk_mul_f32 v[10:11], v[10:11], s[48:49] op_sel_hi:[1,0]
	s_addc_u32 s27, s91, s5
	v_mul_hi_i32 v7, v162, s29
	v_lshlrev_b32_e32 v14, 3, v4
	v_lshlrev_b32_e32 v38, 3, v6
	v_pk_mul_f32 v[36:37], v[36:37], s[48:49] op_sel_hi:[1,0]
	v_pk_mul_f32 v[12:13], v[12:13], s[48:49] op_sel_hi:[1,0]
	v_cvt_pk_bf16_f32 v72, v8, v9
	v_cvt_pk_bf16_f32 v74, v10, v11
	v_lshrrev_b32_e32 v8, 31, v7
	v_ashrrev_i32_e32 v7, 1, v7
	v_mov_b64_e32 v[10:11], s[26:27]
	v_ashrrev_i32_e32 v15, 31, v14
	v_ashrrev_i32_e32 v39, 31, v38
	v_cvt_pk_bf16_f32 v64, v36, v37
	v_cvt_pk_bf16_f32 v68, v12, v13
	v_add_u32_e32 v7, v7, v8
	v_mad_i64_i32 v[12:13], s[26:27], v45, s17, v[10:11]
	v_lshlrev_b64 v[14:15], 1, v[14:15]
	v_mad_i64_i32 v[36:37], s[26:27], v5, s17, v[10:11]
	v_lshlrev_b64 v[38:39], 1, v[38:39]
	v_mad_u64_u32 v[8:9], s[38:39], v7, -12, v[162:163]
	v_lshl_add_u64 v[12:13], v[12:13], 0, v[14:15]
	v_lshl_add_u64 v[36:37], v[36:37], 0, v[38:39]
	s_barrier
; DI f32x16 zero16() { f32x16 z; for (int i = 0; i < 16; ++i) z[i] = 0.f; return z; }
; DI void phase_attn(const Params& p, int hf, bool skipctx, char* smem, int& rot) {
;     ...
;     f32x16 o[2]; o[0] = zero16(); o[1] = zero16();
;     float m_run = -1e30f, l_run = 0.f;
;     uint4 ak0, ak1, ak2, av0, av1, bk0, bk1, bk2, bv0, bv1;
;     const int kr0 = tid / 12, kc0 = tid - kr0 * 12, kr1 = (tid + 512) / 12, kc1 = (tid + 512) - kr1 * 12, kr2 = (tid + 1024) / 12, kc2 = (tid + 1024) - kr2 * 12;
;     const int vr0 = tid >> 4, vr1 = (tid + 512) >> 4, vc = tid & 15;
;     ...
;     __syncthreads();
;     ATT_LOAD(ak0, ak1, ak2, av0, av1, 0);
;     ATT_LOAD(bk0, bk1, bk2, bv0, bv1, 1);
;     ATT_WRITE(ak0, ak1, ak2, av0, av1, 0);
;     __syncthreads();
	global_load_dwordx4 v[76:79], v[12:13], off
	global_load_dwordx4 v[80:83], v[36:37], off
	v_lshlrev_b32_e32 v36, 3, v8
	s_mul_i32 s15, s4, 0x88000
	v_readlane_b32 s36, v252, 5
	v_ashrrev_i32_e32 v37, 31, v36
	s_mul_hi_i32 s5, s4, 0x88000
	v_readlane_b32 s37, v252, 6
	s_add_u32 s36, s36, s15
	v_mad_i64_i32 v[12:13], s[26:27], v7, s17, v[10:11]
	v_lshlrev_b64 v[36:37], 1, v[36:37]
	s_addc_u32 s37, s37, s5
	v_lshl_add_u64 v[12:13], v[12:13], 0, v[36:37]
	v_mov_b32_e32 v40, v42
	v_mov_b32_e32 v41, v16
	v_mov_b32_e32 v16, v43
	v_ashrrev_i32_e32 v9, 4, v160
	v_ashrrev_i32_e32 v50, 4, v164
	global_load_dwordx4 v[84:87], v[12:13], off
	v_mov_b64_e32 v[12:13], s[36:37]
	v_lshlrev_b32_e32 v165, 4, v160
	v_cvt_pk_bf16_f32 v100, v20, v21
	v_add_u32_e32 v20, 0x80, v5
	v_pk_add_f32 v[16:17], v[40:41], v[16:17] neg_lo:[0,1] neg_hi:[0,1]
	v_mad_i64_i32 v[40:41], s[26:27], v9, s16, v[12:13]
	v_and_b32_e32 v42, 0xf0, v165
	v_mov_b32_e32 v43, v221
	v_mad_i64_i32 v[12:13], s[26:27], v50, s16, v[12:13]
	v_cvt_pk_bf16_f32 v98, v18, v19
	v_cvt_pk_bf16_f32 v102, v22, v23
	v_add_u32_e32 v18, 0x80, v45
	v_mad_i64_i32 v[20:21], s[26:27], v20, s17, v[10:11]
	v_add_u32_e32 v22, 0x80, v7
	v_lshl_add_u64 v[40:41], v[40:41], 0, v[42:43]
	v_lshl_add_u64 v[12:13], v[12:13], 0, v[42:43]
	v_mad_i64_i32 v[18:19], s[26:27], v18, s17, v[10:11]
	v_lshl_add_u64 v[20:21], v[20:21], 0, v[38:39]
	v_mad_i64_i32 v[10:11], s[26:27], v22, s17, v[10:11]
	global_load_dwordx4 v[92:95], v[40:41], off
	global_load_dwordx4 v[104:107], v[12:13], off
	v_lshl_add_u64 v[18:19], v[18:19], 0, v[14:15]
	v_lshl_add_u64 v[10:11], v[10:11], 0, v[36:37]
	global_load_dwordx4 v[108:111], v[20:21], off
	global_load_dwordx4 v[116:119], v[10:11], off
	global_load_dwordx4 v[120:123], v[40:41], off offset:256
	global_load_dwordx4 v[112:115], v[18:19], off
	global_load_dwordx4 v[124:127], v[12:13], off offset:256
	v_lshlrev_b32_e32 v46, 16, v0
	v_and_b32_e32 v47, 0xffff0000, v0
	v_lshlrev_b32_e32 v0, 16, v1
	v_and_b32_e32 v1, 0xffff0000, v1
	v_pk_mul_f32 v[30:31], v[30:31], s[48:49] op_sel_hi:[1,0]
	v_pk_add_f32 v[32:33], v[48:49], v[32:33] neg_lo:[0,1] neg_hi:[0,1]
	v_pk_mul_f32 v[0:1], v[0:1], s[48:49] op_sel_hi:[1,0]
	v_lshlrev_b32_e32 v48, 16, v2
	v_and_b32_e32 v49, 0xffff0000, v2
	v_lshlrev_b32_e32 v2, 16, v3
	v_and_b32_e32 v3, 0xffff0000, v3
	v_pk_mul_f32 v[2:3], v[2:3], s[48:49] op_sel_hi:[1,0]
	v_cvt_pk_bf16_f32 v89, v0, v1
	v_pk_mul_f32 v[0:1], v[30:31], v[24:25] op_sel:[0,1] op_sel_hi:[1,0]
	v_cvt_pk_bf16_f32 v91, v2, v3
	v_mov_b32_e32 v2, v28
	v_mov_b32_e32 v3, v0
	v_mov_b32_e32 v0, v29
	v_pk_add_f32 v[0:1], v[2:3], v[0:1] neg_lo:[0,1] neg_hi:[0,1]
	v_pk_mul_f32 v[2:3], v[30:31], v[24:25]
	v_mul_lo_u32 v10, v45, s97
	v_mov_b32_e32 v24, v26
	v_mov_b32_e32 v25, v2
	v_mov_b32_e32 v2, v27
	v_add_u32_e32 v10, 0, v10
	v_lshlrev_b32_e32 v4, 4, v4
	v_pk_add_f32 v[2:3], v[24:25], v[2:3]
	v_add_u32_e32 v176, v10, v4
	v_mul_lo_u32 v4, v5, s97
	v_cvt_pk_bf16_f32 v103, v2, v3
	v_mad_i64_i32 v[2:3], s[26:27], v5, s17, 0
	v_add_u32_e32 v4, 0, v4
	v_lshlrev_b32_e32 v5, 4, v6
	v_cvt_pk_bf16_f32 v96, v16, v17
	v_cvt_pk_bf16_f32 v99, v0, v1
	v_mad_i64_i32 v[0:1], s[26:27], v45, s17, 0
	v_mad_i64_i32 v[16:17], s[26:27], v7, s17, 0
	v_add_u32_e32 v177, v4, v5
	v_mul_lo_u32 v4, v7, s97
	v_add_u32_e32 v4, 0, v4
	v_lshlrev_b32_e32 v5, 4, v8
	s_movk_i32 s26, 0x108
	v_add_u32_e32 v178, v4, v5
	v_mul_lo_u32 v4, v9, s26
	v_add_u32_e32 v5, 0, v4
	s_movk_i32 s27, 0x6800
	v_add3_u32 v179, v5, v42, s27
	v_mul_lo_u32 v5, v50, s26
	v_add_u32_e32 v6, 0, v5
	v_add3_u32 v180, v6, v42, s27
	v_or_b32_e32 v181, 32, v161
	v_or_b32_e32 v182, 64, v161
	v_or_b32_e32 v183, 0x60, v161
	v_readlane_b32 s27, v254, 35
	v_mul_u32_u24_e32 v19, 0x108, v44
	v_mad_u32_u24 v18, v44, s97, 0
	v_add_u32_e32 v21, s27, v4
	v_add_u32_e32 v22, s27, v5
	v_add_u32_e32 v23, s27, v161
	v_add_u32_e32 v24, s27, v181
	v_mov_b32_e32 v4, s27
	v_add_u32_e32 v25, s27, v182
	v_add_u32_e32 v26, s27, v183
	v_readlane_b32 s27, v254, 36
	v_mad_u32_u24 v184, v44, s26, v4
	v_add_u32_e32 v20, 0, v161
	v_mov_b32_e32 v4, s27
	v_mad_u32_u24 v185, v44, s26, v4
	s_add_u32 s26, s15, 0x1a49c300
	v_add_u32_e32 v27, s27, v161
	v_add_u32_e32 v28, s27, v181
	v_add_u32_e32 v29, s27, v182
	v_add_u32_e32 v30, s27, v183
	s_addc_u32 s27, s5, 0
	v_mov_b64_e32 v[4:5], s[26:27]
	v_mad_i64_i32 v[166:167], s[26:27], v9, s16, v[4:5]
	v_mad_i64_i32 v[168:169], s[26:27], v50, s16, v[4:5]
	v_mad_i64_i32 v[4:5], s[26:27], s4, v231, v[16:17]
	v_mad_i64_i32 v[2:3], s[26:27], s4, v231, v[2:3]
	v_mad_i64_i32 v[0:1], s[4:5], s4, v231, v[0:1]
	v_lshl_add_u64 v[174:175], v[0:1], 0, v[14:15]
	v_mov_b32_e32 v14, v221
	v_mov_b32_e32 v15, v221
	v_add_u32_e32 v186, v21, v42
	v_add_u32_e32 v187, v22, v42
	v_add_u32_e32 v188, v23, v19
	v_add_u32_e32 v16, v24, v19
	v_add_u32_e32 v17, v25, v19
	v_add_u32_e32 v21, v26, v19
	v_add_u32_e32 v22, v28, v19
	v_add_u32_e32 v23, v29, v19
	v_add_u32_e32 v24, v30, v19
	v_pk_mul_f32 v[46:47], v[46:47], s[48:49] op_sel_hi:[1,0]
	v_pk_mul_f32 v[48:49], v[48:49], s[48:49] op_sel_hi:[1,0]
	v_lshl_add_u64 v[170:171], v[4:5], 0, v[36:37]
	v_lshl_add_u64 v[172:173], v[2:3], 0, v[38:39]
	v_mov_b32_e32 v0, v221
	v_mov_b32_e32 v1, v221
	v_mov_b32_e32 v2, v221
	v_mov_b32_e32 v3, v221
	v_mov_b32_e32 v4, v221
	v_mov_b32_e32 v5, v221
	v_mov_b32_e32 v6, v221
	v_mov_b32_e32 v7, v221
	v_mov_b32_e32 v8, v221
	v_mov_b32_e32 v9, v221
	v_mov_b32_e32 v10, v221
	v_mov_b32_e32 v11, v221
	v_mov_b32_e32 v12, v221
	v_mov_b32_e32 v13, v221
	v_add_u32_e32 v189, v27, v19
	v_add_u32_e32 v190, v18, v220
	v_add_u32_e32 v191, v20, v19
	v_add_u32_e32 v194, 0x2000, v16
	v_add_u32_e32 v204, 0x2000, v17
	v_add_u32_e32 v206, 0x2000, v21
	v_add_u32_e32 v208, 0x2000, v22
	v_add_u32_e32 v210, 0x2000, v23
	v_add_u32_e32 v211, 0x2000, v24
	v_mov_b64_e32 v[30:31], v[14:15]
	v_cvt_pk_bf16_f32 v88, v46, v47
	v_cvt_pk_bf16_f32 v90, v48, v49
	v_cvt_pk_bf16_f32 v97, v32, v33
	v_cvt_pk_bf16_f32 v101, v34, v35
	v_or_b32_e32 v166, v166, v42
	v_or_b32_e32 v168, v168, v42
	s_mov_b32 s4, 0
	v_mov_b32_e32 v212, 0xf149f2ca
	v_mov_b32_e32 v213, 0
	v_mov_b64_e32 v[28:29], v[12:13]
	v_mov_b64_e32 v[26:27], v[10:11]
	v_mov_b64_e32 v[24:25], v[8:9]
	v_mov_b64_e32 v[22:23], v[6:7]
	v_mov_b64_e32 v[20:21], v[4:5]
	v_mov_b64_e32 v[18:19], v[2:3]
	v_mov_b64_e32 v[16:17], v[0:1]
	v_and_b32_e32 v200, 15, v192
	v_lshrrev_b32_e32 v201, 4, v192
	v_mul_u32_u24_e32 v179, 0x110, v201
	v_lshrrev_b32_e32 v202, 1, v200
	v_lshl_add_u32 v179, v202, 5, v179
	v_and_b32_e32 v202, 1, v200
	v_lshl_add_u32 v179, v202, 3, v179
	v_add_u32_e32 v179, 0x6800, v179
	v_add_u32_e32 v180, 0x2200, v179
	v_add_u32_e32 v186, 0xac00, v179
	v_add_u32_e32 v187, 0xac00, v180
	v_and_b32_e32 v200, 31, v192
	v_bfe_u32 v201, v192, 5, 1
	v_mul_u32_u24_e32 v191, 0x110, v200
	v_lshl_add_u32 v191, v201, 4, v191
	v_add_u32_e32 v191, 0x6800, v191
	s_waitcnt vmcnt(9)
; DI void phase_attn(const Params& p, int hf, bool skipctx, char* smem, int& rot) {
;     ...
;     ATT_WRITE(ak0, ak1, ak2, av0, av1, 0);
;     __syncthreads();
;     for (int kt = 0; kt < nkt; kt += 2) {
;       if (kt + 2 < nkt) ATT_LOAD(ak0, ak1, ak2, av0, av1, kt + 2);
	ds_write_b128 v176, v[76:79]
	s_waitcnt vmcnt(8)
	ds_write_b128 v177, v[80:83]
	s_waitcnt vmcnt(7)
	ds_write_b128 v178, v[84:87]
	s_waitcnt vmcnt(6)
	ds_write_b64 v179, v[92:93] offset:0
	ds_write_b64 v179, v[94:95] offset:16
	s_waitcnt vmcnt(5)
	ds_write_b64 v179, v[104:105] offset:8704
	ds_write_b64 v179, v[106:107] offset:8720
	s_waitcnt lgkmcnt(0)
	s_barrier
	v_mov_b32_e32 v194, v176
	v_mov_b32_e32 v204, v177
	v_mov_b32_e32 v206, v178
	v_mov_b32_e32 v208, v179
	v_mov_b32_e32 v210, v190
	v_mov_b32_e32 v211, v191
	v_mov_b32_e32 v220, 0xf149f2ca
	v_mov_b32_e32 v176, 0
	v_mov_b32_e32 v177, 0
	v_mov_b32_e32 v178, 0
	v_mov_b32_e32 v179, 0
	v_mov_b32_e32 v180, 0
	v_mov_b32_e32 v181, 0
	v_mov_b32_e32 v182, 0
	v_mov_b32_e32 v183, 0
	v_mov_b32_e32 v184, 0
	v_mov_b32_e32 v185, 0
	v_mov_b32_e32 v186, 0
	v_mov_b32_e32 v187, 0
	v_mov_b32_e32 v188, 0
	v_mov_b32_e32 v189, 0
	v_mov_b32_e32 v190, 0
	v_mov_b32_e32 v191, 0
	v_add_u32_e32 v170, 0x18b28000, v170
	v_add_u32_e32 v172, 0x18b28000, v172
	v_add_u32_e32 v174, 0x18b28000, v174
